# xcd barrier: last XCD leader releases all XCDs' workgroups directly (one hop fewer per grid barrier)
# speedup vs baseline: 1.0589x; 1.0009x over previous
; __device__ __forceinline__ unsigned xb_ld(unsigned* p)              { return __hip_atomic_load(p, __ATOMIC_RELAXED, __HIP_MEMORY_SCOPE_AGENT); }
; __device__ __forceinline__ unsigned xb_add(unsigned* p, unsigned v) { return __hip_atomic_fetch_add(p, v, __ATOMIC_RELAXED, __HIP_MEMORY_SCOPE_AGENT); }
; #define XB_SPIN(cond, bar) do { unsigned _sp = 0; while (cond) { __builtin_amdgcn_s_sleep(1); \
;     if ((++_sp & 255u) == 0u) { if (xb_ld(&(bar)[XB_TMO])) break; if (_sp > XB_SPIN_CAP) { atomicAdd(&(bar)[XB_TMO], 1u); break; } } } } while (0)
; __device__ __forceinline__ void xcd_barrier(const XcdBarrier& b) {
;     ...
;             const unsigned og = xb_add(&bar[XB_TOP], 1u);
;             const unsigned tg = og / nx;
;             if (og + 1u == (tg + 1u) * nx) xb_add(&bar[XB_TOPGEN], 1u);
;             else XB_SPIN(xb_ld(&bar[XB_TOPGEN]) == tg, bar);
;             __builtin_amdgcn_fence(__ATOMIC_ACQUIRE, "agent");
;             xb_add(&bar[XB_XGEN(b.x)], 1u);
.LBB0_144:
	s_or_b64 exec, exec, s[12:13]
	v_cvt_f32_u32_e32 v3, v0
	s_waitcnt vmcnt(0)
	v_readfirstlane_b32 s4, v2
	s_add_u32 s12, s66, 0x7500
	s_addc_u32 s13, s67, 0
	v_rcp_iflag_f32_e32 v3, v3
	v_add_u32_e32 v1, s4, v1
	v_add_u32_e32 v4, 1, v1
	s_mov_b64 s[14:15], -1
	v_mul_f32_e32 v2, 0x4f7ffffe, v3
	v_cvt_u32_f32_e32 v2, v2
	v_sub_u32_e32 v3, 0, v0
	v_mul_lo_u32 v3, v3, v2
	v_mul_hi_u32 v3, v2, v3
	v_add_u32_e32 v2, v2, v3
	v_mul_hi_u32 v2, v1, v2
	v_mul_lo_u32 v3, v2, v0
	v_sub_u32_e32 v1, v1, v3
	v_add_u32_e32 v5, 1, v2
	v_cmp_ge_u32_e32 vcc, v1, v0
	v_sub_u32_e32 v3, v1, v0
	s_nop 0
	v_cndmask_b32_e32 v2, v2, v5, vcc
	v_cndmask_b32_e32 v1, v1, v3, vcc
	v_add_u32_e32 v3, 1, v2
	v_cmp_ge_u32_e32 vcc, v1, v0
	s_nop 1
	v_cndmask_b32_e32 v2, v2, v3, vcc
	v_mul_lo_u32 v1, v0, v2
	v_add_u32_e32 v0, v1, v0
	v_cmp_ne_u32_e32 vcc, v4, v0
	v_mov_b64_e32 v[0:1], s[12:13]
	s_cbranch_vccnz .Lxbh0_nl
	v_mov_b32_e32 v2, 1
	global_atomic_add v[0:1], v2, off
	v_subrev_co_u32_e32 v0, vcc, 0x1100, v0
	v_subbrev_co_u32_e32 v1, vcc, 0, v1, vcc
	global_atomic_add v[0:1], v2, off
	global_atomic_add v[0:1], v2, off offset:256
	global_atomic_add v[0:1], v2, off offset:512
	global_atomic_add v[0:1], v2, off offset:768
	global_atomic_add v[0:1], v2, off offset:1024
	global_atomic_add v[0:1], v2, off offset:1280
	global_atomic_add v[0:1], v2, off offset:1536
	global_atomic_add v[0:1], v2, off offset:1792
	global_atomic_add v[0:1], v2, off offset:2048
	global_atomic_add v[0:1], v2, off offset:2304
	global_atomic_add v[0:1], v2, off offset:2560
	global_atomic_add v[0:1], v2, off offset:2816
	global_atomic_add v[0:1], v2, off offset:3072
	global_atomic_add v[0:1], v2, off offset:3328
	global_atomic_add v[0:1], v2, off offset:3584
	global_atomic_add v[0:1], v2, off offset:3840
	s_mov_b64 s[4:5], exec
	s_branch .LBB0_158
.Lxbh0_nl:
	s_and_saveexec_b64 s[4:5], vcc
	s_cbranch_execz .LBB0_156
	v_mov_b32_e32 v0, 0
	global_load_dword v1, v0, s[12:13] sc1
	s_mov_b64 s[18:19], 0
	s_waitcnt vmcnt(0)
	v_cmp_eq_u32_e32 vcc, v1, v2
	s_and_saveexec_b64 s[16:17], vcc
	s_cbranch_execz .LBB0_155
	s_add_u32 s14, s66, 0x4200
	s_addc_u32 s15, s67, 0
	s_mov_b32 s28, 1
	s_branch .LBB0_148

; __device__ __forceinline__ unsigned xb_add(unsigned* p, unsigned v) { return __hip_atomic_fetch_add(p, v, __ATOMIC_RELAXED, __HIP_MEMORY_SCOPE_AGENT); }
; __device__ __forceinline__ void xcd_barrier(const XcdBarrier& b) {
;     ...
;             __builtin_amdgcn_fence(__ATOMIC_ACQUIRE, "agent");
;             xb_add(&bar[XB_XGEN(b.x)], 1u);
.LBB0_158:
	s_or_b64 exec, exec, s[4:5]
	s_mov_b64 s[4:5], exec
	v_mbcnt_lo_u32_b32 v0, s4, 0
	v_mbcnt_hi_u32_b32 v0, s5, v0
	v_cmp_eq_u32_e32 vcc, 0, v0
	s_waitcnt vmcnt(0)
	buffer_inv sc1
	s_waitcnt vmcnt(0)

; __device__ __forceinline__ unsigned xb_ld(unsigned* p)              { return __hip_atomic_load(p, __ATOMIC_RELAXED, __HIP_MEMORY_SCOPE_AGENT); }
; __device__ __forceinline__ unsigned xb_add(unsigned* p, unsigned v) { return __hip_atomic_fetch_add(p, v, __ATOMIC_RELAXED, __HIP_MEMORY_SCOPE_AGENT); }
; #define XB_SPIN(cond, bar) do { unsigned _sp = 0; while (cond) { __builtin_amdgcn_s_sleep(1); \
;     if ((++_sp & 255u) == 0u) { if (xb_ld(&(bar)[XB_TMO])) break; if (_sp > XB_SPIN_CAP) { atomicAdd(&(bar)[XB_TMO], 1u); break; } } } } while (0)
; __device__ __forceinline__ void xcd_barrier(const XcdBarrier& b) {
;     ...
;             const unsigned og = xb_add(&bar[XB_TOP], 1u);
;             const unsigned tg = og / nx;
;             if (og + 1u == (tg + 1u) * nx) xb_add(&bar[XB_TOPGEN], 1u);
;             else XB_SPIN(xb_ld(&bar[XB_TOPGEN]) == tg, bar);
;             __builtin_amdgcn_fence(__ATOMIC_ACQUIRE, "agent");
;             xb_add(&bar[XB_XGEN(b.x)], 1u);
.LBB0_1005:
	s_or_b64 exec, exec, s[16:17]
	v_cvt_f32_u32_e32 v3, v0
	s_waitcnt vmcnt(0)
	v_readfirstlane_b32 s10, v2
	s_add_u32 s16, s66, 0x7500
	s_addc_u32 s17, s67, 0
	v_rcp_iflag_f32_e32 v3, v3
	v_add_u32_e32 v1, s10, v1
	v_add_u32_e32 v4, 1, v1
	s_mov_b64 s[18:19], -1
	v_mul_f32_e32 v2, 0x4f7ffffe, v3
	v_cvt_u32_f32_e32 v2, v2
	v_sub_u32_e32 v3, 0, v0
	v_mul_lo_u32 v3, v3, v2
	v_mul_hi_u32 v3, v2, v3
	v_add_u32_e32 v2, v2, v3
	v_mul_hi_u32 v2, v1, v2
	v_mul_lo_u32 v3, v2, v0
	v_sub_u32_e32 v1, v1, v3
	v_add_u32_e32 v5, 1, v2
	v_cmp_ge_u32_e32 vcc, v1, v0
	v_sub_u32_e32 v3, v1, v0
	s_nop 0
	v_cndmask_b32_e32 v2, v2, v5, vcc
	v_cndmask_b32_e32 v1, v1, v3, vcc
	v_add_u32_e32 v3, 1, v2
	v_cmp_ge_u32_e32 vcc, v1, v0
	s_nop 1
	v_cndmask_b32_e32 v2, v2, v3, vcc
	v_mul_lo_u32 v1, v0, v2
	v_add_u32_e32 v0, v1, v0
	v_cmp_ne_u32_e32 vcc, v4, v0
	v_mov_b64_e32 v[0:1], s[16:17]
	s_cbranch_vccnz .Lxbh2_nl
	v_mov_b32_e32 v2, 1
	global_atomic_add v[0:1], v2, off
	v_subrev_co_u32_e32 v0, vcc, 0x1100, v0
	v_subbrev_co_u32_e32 v1, vcc, 0, v1, vcc
	global_atomic_add v[0:1], v2, off
	global_atomic_add v[0:1], v2, off offset:256
	global_atomic_add v[0:1], v2, off offset:512
	global_atomic_add v[0:1], v2, off offset:768
	global_atomic_add v[0:1], v2, off offset:1024
	global_atomic_add v[0:1], v2, off offset:1280
	global_atomic_add v[0:1], v2, off offset:1536
	global_atomic_add v[0:1], v2, off offset:1792
	global_atomic_add v[0:1], v2, off offset:2048
	global_atomic_add v[0:1], v2, off offset:2304
	global_atomic_add v[0:1], v2, off offset:2560
	global_atomic_add v[0:1], v2, off offset:2816
	global_atomic_add v[0:1], v2, off offset:3072
	global_atomic_add v[0:1], v2, off offset:3328
	global_atomic_add v[0:1], v2, off offset:3584
	global_atomic_add v[0:1], v2, off offset:3840
	s_mov_b64 s[10:11], exec
	s_branch .LBB0_1019
.Lxbh2_nl:
	s_and_saveexec_b64 s[10:11], vcc
	s_cbranch_execz .LBB0_1017
	v_mov_b32_e32 v0, 0
	global_load_dword v1, v0, s[16:17] sc1
	s_mov_b64 s[22:23], 0
	s_waitcnt vmcnt(0)
	v_cmp_eq_u32_e32 vcc, v1, v2
	s_and_saveexec_b64 s[20:21], vcc
	s_cbranch_execz .LBB0_1016
	s_add_u32 s18, s66, 0x4200
	s_addc_u32 s19, s67, 0
	s_mov_b32 s33, 1
	s_branch .LBB0_1009

; __device__ __forceinline__ unsigned xb_add(unsigned* p, unsigned v) { return __hip_atomic_fetch_add(p, v, __ATOMIC_RELAXED, __HIP_MEMORY_SCOPE_AGENT); }
; __device__ __forceinline__ void xcd_barrier(const XcdBarrier& b) {
;     ...
;             __builtin_amdgcn_fence(__ATOMIC_ACQUIRE, "agent");
;             xb_add(&bar[XB_XGEN(b.x)], 1u);
.LBB0_1019:
	s_or_b64 exec, exec, s[10:11]
	s_mov_b64 s[10:11], exec
	v_mbcnt_lo_u32_b32 v0, s10, 0
	v_mbcnt_hi_u32_b32 v0, s11, v0
	v_cmp_eq_u32_e32 vcc, 0, v0
	s_waitcnt vmcnt(0)
	buffer_inv sc1
	s_waitcnt vmcnt(0)

; __device__ __forceinline__ unsigned xb_ld(unsigned* p)              { return __hip_atomic_load(p, __ATOMIC_RELAXED, __HIP_MEMORY_SCOPE_AGENT); }
; __device__ __forceinline__ unsigned xb_add(unsigned* p, unsigned v) { return __hip_atomic_fetch_add(p, v, __ATOMIC_RELAXED, __HIP_MEMORY_SCOPE_AGENT); }
; #define XB_SPIN(cond, bar) do { unsigned _sp = 0; while (cond) { __builtin_amdgcn_s_sleep(1); \
;     if ((++_sp & 255u) == 0u) { if (xb_ld(&(bar)[XB_TMO])) break; if (_sp > XB_SPIN_CAP) { atomicAdd(&(bar)[XB_TMO], 1u); break; } } } } while (0)
; __device__ __forceinline__ void xcd_barrier(const XcdBarrier& b) {
;     ...
;             const unsigned og = xb_add(&bar[XB_TOP], 1u);
;             const unsigned tg = og / nx;
;             if (og + 1u == (tg + 1u) * nx) xb_add(&bar[XB_TOPGEN], 1u);
;             else XB_SPIN(xb_ld(&bar[XB_TOPGEN]) == tg, bar);
;             __builtin_amdgcn_fence(__ATOMIC_ACQUIRE, "agent");
;             xb_add(&bar[XB_XGEN(b.x)], 1u);
.LBB0_1081:
	s_or_b64 exec, exec, s[8:9]
	v_cvt_f32_u32_e32 v3, v0
	s_waitcnt vmcnt(0)
	v_readfirstlane_b32 s6, v2
	s_add_u32 s8, s66, 0x7500
	s_addc_u32 s9, s67, 0
	v_rcp_iflag_f32_e32 v3, v3
	v_add_u32_e32 v1, s6, v1
	v_add_u32_e32 v4, 1, v1
	s_mov_b64 s[10:11], -1
	v_mul_f32_e32 v2, 0x4f7ffffe, v3
	v_cvt_u32_f32_e32 v2, v2
	v_sub_u32_e32 v3, 0, v0
	v_mul_lo_u32 v3, v3, v2
	v_mul_hi_u32 v3, v2, v3
	v_add_u32_e32 v2, v2, v3
	v_mul_hi_u32 v2, v1, v2
	v_mul_lo_u32 v3, v2, v0
	v_sub_u32_e32 v1, v1, v3
	v_add_u32_e32 v5, 1, v2
	v_cmp_ge_u32_e32 vcc, v1, v0
	v_sub_u32_e32 v3, v1, v0
	s_nop 0
	v_cndmask_b32_e32 v2, v2, v5, vcc
	v_cndmask_b32_e32 v1, v1, v3, vcc
	v_add_u32_e32 v3, 1, v2
	v_cmp_ge_u32_e32 vcc, v1, v0
	s_nop 1
	v_cndmask_b32_e32 v2, v2, v3, vcc
	v_mul_lo_u32 v1, v0, v2
	v_add_u32_e32 v0, v1, v0
	v_cmp_ne_u32_e32 vcc, v4, v0
	v_mov_b64_e32 v[0:1], s[8:9]
	s_cbranch_vccnz .Lxbh3_nl
	v_mov_b32_e32 v2, 1
	global_atomic_add v[0:1], v2, off
	v_subrev_co_u32_e32 v0, vcc, 0x1100, v0
	v_subbrev_co_u32_e32 v1, vcc, 0, v1, vcc
	global_atomic_add v[0:1], v2, off
	global_atomic_add v[0:1], v2, off offset:256
	global_atomic_add v[0:1], v2, off offset:512
	global_atomic_add v[0:1], v2, off offset:768
	global_atomic_add v[0:1], v2, off offset:1024
	global_atomic_add v[0:1], v2, off offset:1280
	global_atomic_add v[0:1], v2, off offset:1536
	global_atomic_add v[0:1], v2, off offset:1792
	global_atomic_add v[0:1], v2, off offset:2048
	global_atomic_add v[0:1], v2, off offset:2304
	global_atomic_add v[0:1], v2, off offset:2560
	global_atomic_add v[0:1], v2, off offset:2816
	global_atomic_add v[0:1], v2, off offset:3072
	global_atomic_add v[0:1], v2, off offset:3328
	global_atomic_add v[0:1], v2, off offset:3584
	global_atomic_add v[0:1], v2, off offset:3840
	s_mov_b64 s[6:7], exec
	s_branch .LBB0_1095
.Lxbh3_nl:
	s_and_saveexec_b64 s[6:7], vcc
	s_cbranch_execz .LBB0_1093
	v_mov_b32_e32 v0, 0
	global_load_dword v1, v0, s[8:9] sc1
	s_mov_b64 s[16:17], 0
	s_waitcnt vmcnt(0)
	v_cmp_eq_u32_e32 vcc, v1, v2
	s_and_saveexec_b64 s[14:15], vcc
	s_cbranch_execz .LBB0_1092
	s_add_u32 s10, s66, 0x4200
	s_addc_u32 s11, s67, 0
	s_mov_b32 s26, 1
	s_branch .LBB0_1085

; __device__ __forceinline__ unsigned xb_add(unsigned* p, unsigned v) { return __hip_atomic_fetch_add(p, v, __ATOMIC_RELAXED, __HIP_MEMORY_SCOPE_AGENT); }
; __device__ __forceinline__ void xcd_barrier(const XcdBarrier& b) {
;     ...
;             __builtin_amdgcn_fence(__ATOMIC_ACQUIRE, "agent");
;             xb_add(&bar[XB_XGEN(b.x)], 1u);
.LBB0_1095:
	s_or_b64 exec, exec, s[6:7]
	s_mov_b64 s[6:7], exec
	v_mbcnt_lo_u32_b32 v0, s6, 0
	v_mbcnt_hi_u32_b32 v0, s7, v0
	v_cmp_eq_u32_e32 vcc, 0, v0
	s_waitcnt vmcnt(0)
	buffer_inv sc1
	s_waitcnt vmcnt(0)

; __device__ __forceinline__ unsigned xb_ld(unsigned* p)              { return __hip_atomic_load(p, __ATOMIC_RELAXED, __HIP_MEMORY_SCOPE_AGENT); }
; __device__ __forceinline__ unsigned xb_add(unsigned* p, unsigned v) { return __hip_atomic_fetch_add(p, v, __ATOMIC_RELAXED, __HIP_MEMORY_SCOPE_AGENT); }
; #define XB_SPIN(cond, bar) do { unsigned _sp = 0; while (cond) { __builtin_amdgcn_s_sleep(1); \
;     if ((++_sp & 255u) == 0u) { if (xb_ld(&(bar)[XB_TMO])) break; if (_sp > XB_SPIN_CAP) { atomicAdd(&(bar)[XB_TMO], 1u); break; } } } } while (0)
; __device__ __forceinline__ void xcd_barrier(const XcdBarrier& b) {
;     ...
;             const unsigned og = xb_add(&bar[XB_TOP], 1u);
;             const unsigned tg = og / nx;
;             if (og + 1u == (tg + 1u) * nx) xb_add(&bar[XB_TOPGEN], 1u);
;             else XB_SPIN(xb_ld(&bar[XB_TOPGEN]) == tg, bar);
;             __builtin_amdgcn_fence(__ATOMIC_ACQUIRE, "agent");
;             xb_add(&bar[XB_XGEN(b.x)], 1u);
.LBB0_1261:
	s_or_b64 exec, exec, s[10:11]
	v_cvt_f32_u32_e32 v3, v0
	s_waitcnt vmcnt(0)
	v_readfirstlane_b32 s8, v2
	s_add_u32 s10, s66, 0x7500
	s_addc_u32 s11, s67, 0
	v_rcp_iflag_f32_e32 v3, v3
	v_add_u32_e32 v1, s8, v1
	v_add_u32_e32 v4, 1, v1
	s_mov_b64 s[12:13], -1
	v_mul_f32_e32 v2, 0x4f7ffffe, v3
	v_cvt_u32_f32_e32 v2, v2
	v_sub_u32_e32 v3, 0, v0
	v_mul_lo_u32 v3, v3, v2
	v_mul_hi_u32 v3, v2, v3
	v_add_u32_e32 v2, v2, v3
	v_mul_hi_u32 v2, v1, v2
	v_mul_lo_u32 v3, v2, v0
	v_sub_u32_e32 v1, v1, v3
	v_add_u32_e32 v5, 1, v2
	v_cmp_ge_u32_e32 vcc, v1, v0
	v_sub_u32_e32 v3, v1, v0
	s_nop 0
	v_cndmask_b32_e32 v2, v2, v5, vcc
	v_cndmask_b32_e32 v1, v1, v3, vcc
	v_add_u32_e32 v3, 1, v2
	v_cmp_ge_u32_e32 vcc, v1, v0
	s_nop 1
	v_cndmask_b32_e32 v2, v2, v3, vcc
	v_mul_lo_u32 v1, v0, v2
	v_add_u32_e32 v0, v1, v0
	v_cmp_ne_u32_e32 vcc, v4, v0
	v_mov_b64_e32 v[0:1], s[10:11]
	s_cbranch_vccnz .Lxbh4_nl
	v_mov_b32_e32 v2, 1
	global_atomic_add v[0:1], v2, off
	v_subrev_co_u32_e32 v0, vcc, 0x1100, v0
	v_subbrev_co_u32_e32 v1, vcc, 0, v1, vcc
	global_atomic_add v[0:1], v2, off
	global_atomic_add v[0:1], v2, off offset:256
	global_atomic_add v[0:1], v2, off offset:512
	global_atomic_add v[0:1], v2, off offset:768
	global_atomic_add v[0:1], v2, off offset:1024
	global_atomic_add v[0:1], v2, off offset:1280
	global_atomic_add v[0:1], v2, off offset:1536
	global_atomic_add v[0:1], v2, off offset:1792
	global_atomic_add v[0:1], v2, off offset:2048
	global_atomic_add v[0:1], v2, off offset:2304
	global_atomic_add v[0:1], v2, off offset:2560
	global_atomic_add v[0:1], v2, off offset:2816
	global_atomic_add v[0:1], v2, off offset:3072
	global_atomic_add v[0:1], v2, off offset:3328
	global_atomic_add v[0:1], v2, off offset:3584
	global_atomic_add v[0:1], v2, off offset:3840
	s_mov_b64 s[8:9], exec
	s_branch .LBB0_1275
.Lxbh4_nl:
	s_and_saveexec_b64 s[8:9], vcc
	s_cbranch_execz .LBB0_1273
	v_mov_b32_e32 v0, 0
	global_load_dword v1, v0, s[10:11] sc1
	s_mov_b64 s[16:17], 0
	s_waitcnt vmcnt(0)
	v_cmp_eq_u32_e32 vcc, v1, v2
	s_and_saveexec_b64 s[14:15], vcc
	s_cbranch_execz .LBB0_1272
	s_add_u32 s12, s66, 0x4200
	s_addc_u32 s13, s67, 0
	s_mov_b32 s26, 1
	s_branch .LBB0_1265

; __device__ __forceinline__ unsigned xb_add(unsigned* p, unsigned v) { return __hip_atomic_fetch_add(p, v, __ATOMIC_RELAXED, __HIP_MEMORY_SCOPE_AGENT); }
; __device__ __forceinline__ void xcd_barrier(const XcdBarrier& b) {
;     ...
;             __builtin_amdgcn_fence(__ATOMIC_ACQUIRE, "agent");
;             xb_add(&bar[XB_XGEN(b.x)], 1u);
.LBB0_1275:
	s_or_b64 exec, exec, s[8:9]
	s_mov_b64 s[8:9], exec
	v_mbcnt_lo_u32_b32 v0, s8, 0
	v_mbcnt_hi_u32_b32 v0, s9, v0
	v_cmp_eq_u32_e32 vcc, 0, v0
	s_waitcnt vmcnt(0)
	buffer_inv sc1
	s_waitcnt vmcnt(0)

; __device__ __forceinline__ unsigned xb_ld(unsigned* p)              { return __hip_atomic_load(p, __ATOMIC_RELAXED, __HIP_MEMORY_SCOPE_AGENT); }
; #define XB_SPIN(cond, bar) do { unsigned _sp = 0; while (cond) { __builtin_amdgcn_s_sleep(1); \
;     if ((++_sp & 255u) == 0u) { if (xb_ld(&(bar)[XB_TMO])) break; if (_sp > XB_SPIN_CAP) { atomicAdd(&(bar)[XB_TMO], 1u); break; } } } } while (0)
; __device__ __forceinline__ void xcd_barrier(const XcdBarrier& b) {
;     ...
;             else XB_SPIN(xb_ld(&bar[XB_TOPGEN]) == tg, bar);
;             __builtin_amdgcn_fence(__ATOMIC_ACQUIRE, "agent");
.Lxbh5_nl:
	s_and_saveexec_b64 s[6:7], vcc
	s_cbranch_execz .LBB0_1330
	v_mov_b32_e32 v0, 0
	global_load_dword v1, v0, s[8:9] sc1
	s_mov_b64 s[14:15], 0
	s_waitcnt vmcnt(0)
	v_cmp_eq_u32_e32 vcc, v1, v2
	s_and_saveexec_b64 s[12:13], vcc
	s_cbranch_execz .LBB0_1329
	s_add_u32 s10, s66, 0x4200
	s_addc_u32 s11, s67, 0
	s_mov_b32 s24, 1
	s_branch .LBB0_1322

; __device__ __forceinline__ unsigned xb_ld(unsigned* p)              { return __hip_atomic_load(p, __ATOMIC_RELAXED, __HIP_MEMORY_SCOPE_AGENT); }
; __device__ __forceinline__ unsigned xb_add(unsigned* p, unsigned v) { return __hip_atomic_fetch_add(p, v, __ATOMIC_RELAXED, __HIP_MEMORY_SCOPE_AGENT); }
; #define XB_SPIN(cond, bar) do { unsigned _sp = 0; while (cond) { __builtin_amdgcn_s_sleep(1); \
;     if ((++_sp & 255u) == 0u) { if (xb_ld(&(bar)[XB_TMO])) break; if (_sp > XB_SPIN_CAP) { atomicAdd(&(bar)[XB_TMO], 1u); break; } } } } while (0)
; __device__ __forceinline__ void xcd_barrier(const XcdBarrier& b) {
;     ...
;             const unsigned og = xb_add(&bar[XB_TOP], 1u);
;             const unsigned tg = og / nx;
;             if (og + 1u == (tg + 1u) * nx) xb_add(&bar[XB_TOPGEN], 1u);
;             else XB_SPIN(xb_ld(&bar[XB_TOPGEN]) == tg, bar);
;             __builtin_amdgcn_fence(__ATOMIC_ACQUIRE, "agent");
;             xb_add(&bar[XB_XGEN(b.x)], 1u);
.LBB0_1580:
	s_or_b64 exec, exec, s[6:7]
	v_cvt_f32_u32_e32 v3, v0
	s_waitcnt vmcnt(0)
	v_readfirstlane_b32 s4, v2
	s_add_u32 s6, s66, 0x7500
	s_addc_u32 s7, s67, 0
	v_rcp_iflag_f32_e32 v3, v3
	v_add_u32_e32 v1, s4, v1
	v_add_u32_e32 v4, 1, v1
	s_mov_b64 s[8:9], -1
	v_mul_f32_e32 v2, 0x4f7ffffe, v3
	v_cvt_u32_f32_e32 v2, v2
	v_sub_u32_e32 v3, 0, v0
	v_mul_lo_u32 v3, v3, v2
	v_mul_hi_u32 v3, v2, v3
	v_add_u32_e32 v2, v2, v3
	v_mul_hi_u32 v2, v1, v2
	v_mul_lo_u32 v3, v2, v0
	v_sub_u32_e32 v1, v1, v3
	v_add_u32_e32 v5, 1, v2
	v_cmp_ge_u32_e32 vcc, v1, v0
	v_sub_u32_e32 v3, v1, v0
	s_nop 0
	v_cndmask_b32_e32 v2, v2, v5, vcc
	v_cndmask_b32_e32 v1, v1, v3, vcc
	v_add_u32_e32 v3, 1, v2
	v_cmp_ge_u32_e32 vcc, v1, v0
	s_nop 1
	v_cndmask_b32_e32 v2, v2, v3, vcc
	v_mul_lo_u32 v1, v0, v2
	v_add_u32_e32 v0, v1, v0
	v_cmp_ne_u32_e32 vcc, v4, v0
	v_mov_b64_e32 v[0:1], s[6:7]
	s_cbranch_vccnz .Lxbh7_nl
	v_mov_b32_e32 v2, 1
	global_atomic_add v[0:1], v2, off
	v_subrev_co_u32_e32 v0, vcc, 0x1100, v0
	v_subbrev_co_u32_e32 v1, vcc, 0, v1, vcc
	global_atomic_add v[0:1], v2, off
	global_atomic_add v[0:1], v2, off offset:256
	global_atomic_add v[0:1], v2, off offset:512
	global_atomic_add v[0:1], v2, off offset:768
	global_atomic_add v[0:1], v2, off offset:1024
	global_atomic_add v[0:1], v2, off offset:1280
	global_atomic_add v[0:1], v2, off offset:1536
	global_atomic_add v[0:1], v2, off offset:1792
	global_atomic_add v[0:1], v2, off offset:2048
	global_atomic_add v[0:1], v2, off offset:2304
	global_atomic_add v[0:1], v2, off offset:2560
	global_atomic_add v[0:1], v2, off offset:2816
	global_atomic_add v[0:1], v2, off offset:3072
	global_atomic_add v[0:1], v2, off offset:3328
	global_atomic_add v[0:1], v2, off offset:3584
	global_atomic_add v[0:1], v2, off offset:3840
	s_mov_b64 s[4:5], exec
	s_branch .LBB0_1594
.Lxbh7_nl:
	s_and_saveexec_b64 s[4:5], vcc
	s_cbranch_execz .LBB0_1592
	v_mov_b32_e32 v0, 0
	global_load_dword v1, v0, s[6:7] sc1
	s_mov_b64 s[12:13], 0
	s_waitcnt vmcnt(0)
	v_cmp_eq_u32_e32 vcc, v1, v2
	s_and_saveexec_b64 s[10:11], vcc
	s_cbranch_execz .LBB0_1591
	s_add_u32 s8, s66, 0x4200
	s_addc_u32 s9, s67, 0
	s_mov_b32 s22, 1
	s_branch .LBB0_1584

; __device__ __forceinline__ unsigned xb_ld(unsigned* p)              { return __hip_atomic_load(p, __ATOMIC_RELAXED, __HIP_MEMORY_SCOPE_AGENT); }
; __device__ __forceinline__ unsigned xb_add(unsigned* p, unsigned v) { return __hip_atomic_fetch_add(p, v, __ATOMIC_RELAXED, __HIP_MEMORY_SCOPE_AGENT); }
; #define XB_SPIN(cond, bar) do { unsigned _sp = 0; while (cond) { __builtin_amdgcn_s_sleep(1); \
;     if ((++_sp & 255u) == 0u) { if (xb_ld(&(bar)[XB_TMO])) break; if (_sp > XB_SPIN_CAP) { atomicAdd(&(bar)[XB_TMO], 1u); break; } } } } while (0)
; __device__ __forceinline__ void xcd_barrier_light(const XcdBarrier& b) {
;     ...
;             const unsigned og = xb_add(&bar[XB_TOP], 1u);
;             const unsigned tg = og / nx;
;             if (og + 1u == (tg + 1u) * nx) xb_add(&bar[XB_TOPGEN], 1u);
;             else XB_SPIN(xb_ld(&bar[XB_TOPGEN]) == tg, bar);
;             xb_add(&bar[XB_XGEN(b.x)], 1u);
.LBB0_1721:
	s_or_b64 exec, exec, s[6:7]
	s_waitcnt lgkmcnt(0)
	v_cvt_f32_u32_e32 v3, v0
	s_waitcnt vmcnt(0)
	v_readfirstlane_b32 s6, v2
	s_add_u32 s8, s66, 0x7500
	s_addc_u32 s9, s67, 0
	v_rcp_iflag_f32_e32 v3, v3
	v_add_u32_e32 v1, s6, v1
	v_add_u32_e32 v4, 1, v1
	s_mov_b64 s[10:11], -1
	v_mul_f32_e32 v2, 0x4f7ffffe, v3
	v_cvt_u32_f32_e32 v2, v2
	v_sub_u32_e32 v3, 0, v0
	v_mul_lo_u32 v3, v3, v2
	v_mul_hi_u32 v3, v2, v3
	v_add_u32_e32 v2, v2, v3
	v_mul_hi_u32 v2, v1, v2
	v_mul_lo_u32 v3, v2, v0
	v_sub_u32_e32 v1, v1, v3
	v_add_u32_e32 v5, 1, v2
	v_cmp_ge_u32_e32 vcc, v1, v0
	v_sub_u32_e32 v3, v1, v0
	s_nop 0
	v_cndmask_b32_e32 v2, v2, v5, vcc
	v_cndmask_b32_e32 v1, v1, v3, vcc
	v_add_u32_e32 v3, 1, v2
	v_cmp_ge_u32_e32 vcc, v1, v0
	s_nop 1
	v_cndmask_b32_e32 v2, v2, v3, vcc
	v_mul_lo_u32 v1, v0, v2
	v_add_u32_e32 v0, v1, v0
	v_cmp_ne_u32_e32 vcc, v4, v0
	v_mov_b64_e32 v[0:1], s[8:9]
	s_cbranch_vccnz .Lxbh8_nl
	v_mov_b32_e32 v2, 1
	global_atomic_add v[0:1], v2, off
	v_subrev_co_u32_e32 v0, vcc, 0x1100, v0
	v_subbrev_co_u32_e32 v1, vcc, 0, v1, vcc
	global_atomic_add v[0:1], v2, off
	global_atomic_add v[0:1], v2, off offset:256
	global_atomic_add v[0:1], v2, off offset:512
	global_atomic_add v[0:1], v2, off offset:768
	global_atomic_add v[0:1], v2, off offset:1024
	global_atomic_add v[0:1], v2, off offset:1280
	global_atomic_add v[0:1], v2, off offset:1536
	global_atomic_add v[0:1], v2, off offset:1792
	global_atomic_add v[0:1], v2, off offset:2048
	global_atomic_add v[0:1], v2, off offset:2304
	global_atomic_add v[0:1], v2, off offset:2560
	global_atomic_add v[0:1], v2, off offset:2816
	global_atomic_add v[0:1], v2, off offset:3072
	global_atomic_add v[0:1], v2, off offset:3328
	global_atomic_add v[0:1], v2, off offset:3584
	global_atomic_add v[0:1], v2, off offset:3840
	s_mov_b64 s[6:7], exec
	s_branch .LBB0_1735

; __device__ __forceinline__ unsigned xb_add(unsigned* p, unsigned v) { return __hip_atomic_fetch_add(p, v, __ATOMIC_RELAXED, __HIP_MEMORY_SCOPE_AGENT); }
; __device__ __forceinline__ void xcd_barrier_light(const XcdBarrier& b) {
;     ...
;             xb_add(&bar[XB_XGEN(b.x)], 1u);
;             asm volatile("s_waitcnt vmcnt(0)" ::: "memory");
.LBB0_1735:
	s_or_b64 exec, exec, s[6:7]
	s_mov_b64 s[8:9], exec
	v_mbcnt_lo_u32_b32 v0, s8, 0
	v_mbcnt_hi_u32_b32 v0, s9, v0
	v_cmp_eq_u32_e32 vcc, 0, v0
	s_waitcnt vmcnt(0)

; __device__ __forceinline__ unsigned xb_ld(unsigned* p)              { return __hip_atomic_load(p, __ATOMIC_RELAXED, __HIP_MEMORY_SCOPE_AGENT); }
; __device__ __forceinline__ unsigned xb_add(unsigned* p, unsigned v) { return __hip_atomic_fetch_add(p, v, __ATOMIC_RELAXED, __HIP_MEMORY_SCOPE_AGENT); }
; #define XB_SPIN(cond, bar) do { unsigned _sp = 0; while (cond) { __builtin_amdgcn_s_sleep(1); \
;     if ((++_sp & 255u) == 0u) { if (xb_ld(&(bar)[XB_TMO])) break; if (_sp > XB_SPIN_CAP) { atomicAdd(&(bar)[XB_TMO], 1u); break; } } } } while (0)
; __device__ __forceinline__ void xcd_barrier_light(const XcdBarrier& b) {
;     ...
;             const unsigned og = xb_add(&bar[XB_TOP], 1u);
;             const unsigned tg = og / nx;
;             if (og + 1u == (tg + 1u) * nx) xb_add(&bar[XB_TOPGEN], 1u);
;             else XB_SPIN(xb_ld(&bar[XB_TOPGEN]) == tg, bar);
;             xb_add(&bar[XB_XGEN(b.x)], 1u);
.LBB0_1992:
	s_or_b64 exec, exec, s[4:5]
	s_waitcnt lgkmcnt(0)
	v_cvt_f32_u32_e32 v3, v0
	s_waitcnt vmcnt(0)
	v_readfirstlane_b32 s4, v2
	s_add_u32 s6, s66, 0x7500
	s_addc_u32 s7, s67, 0
	v_rcp_iflag_f32_e32 v3, v3
	v_add_u32_e32 v1, s4, v1
	v_add_u32_e32 v64, 1, v1
	s_mov_b64 s[8:9], -1
	v_mul_f32_e32 v2, 0x4f7ffffe, v3
	v_cvt_u32_f32_e32 v2, v2
	v_sub_u32_e32 v3, 0, v0
	v_mul_lo_u32 v3, v3, v2
	v_mul_hi_u32 v3, v2, v3
	v_add_u32_e32 v2, v2, v3
	v_mul_hi_u32 v2, v1, v2
	v_mul_lo_u32 v3, v2, v0
	v_sub_u32_e32 v1, v1, v3
	v_add_u32_e32 v65, 1, v2
	v_cmp_ge_u32_e32 vcc, v1, v0
	v_sub_u32_e32 v3, v1, v0
	s_nop 0
	v_cndmask_b32_e32 v2, v2, v65, vcc
	v_cndmask_b32_e32 v1, v1, v3, vcc
	v_add_u32_e32 v3, 1, v2
	v_cmp_ge_u32_e32 vcc, v1, v0
	s_nop 1
	v_cndmask_b32_e32 v2, v2, v3, vcc
	v_mul_lo_u32 v1, v0, v2
	v_add_u32_e32 v0, v1, v0
	v_cmp_ne_u32_e32 vcc, v64, v0
	v_mov_b64_e32 v[0:1], s[6:7]
	s_cbranch_vccnz .Lxbh11_nl
	v_mov_b32_e32 v2, 1
	global_atomic_add v[0:1], v2, off
	v_subrev_co_u32_e32 v0, vcc, 0x1100, v0
	v_subbrev_co_u32_e32 v1, vcc, 0, v1, vcc
	global_atomic_add v[0:1], v2, off
	global_atomic_add v[0:1], v2, off offset:256
	global_atomic_add v[0:1], v2, off offset:512
	global_atomic_add v[0:1], v2, off offset:768
	global_atomic_add v[0:1], v2, off offset:1024
	global_atomic_add v[0:1], v2, off offset:1280
	global_atomic_add v[0:1], v2, off offset:1536
	global_atomic_add v[0:1], v2, off offset:1792
	global_atomic_add v[0:1], v2, off offset:2048
	global_atomic_add v[0:1], v2, off offset:2304
	global_atomic_add v[0:1], v2, off offset:2560
	global_atomic_add v[0:1], v2, off offset:2816
	global_atomic_add v[0:1], v2, off offset:3072
	global_atomic_add v[0:1], v2, off offset:3328
	global_atomic_add v[0:1], v2, off offset:3584
	global_atomic_add v[0:1], v2, off offset:3840
	s_mov_b64 s[4:5], exec
	s_branch .LBB0_2006

; __device__ __forceinline__ unsigned xb_add(unsigned* p, unsigned v) { return __hip_atomic_fetch_add(p, v, __ATOMIC_RELAXED, __HIP_MEMORY_SCOPE_AGENT); }
; __device__ __forceinline__ void xcd_barrier_light(const XcdBarrier& b) {
;     ...
;             xb_add(&bar[XB_XGEN(b.x)], 1u);
;             asm volatile("s_waitcnt vmcnt(0)" ::: "memory");
.LBB0_2006:
	s_or_b64 exec, exec, s[4:5]
	s_mov_b64 s[6:7], exec
	v_mbcnt_lo_u32_b32 v0, s6, 0
	v_mbcnt_hi_u32_b32 v0, s7, v0
	v_cmp_eq_u32_e32 vcc, 0, v0
	s_waitcnt vmcnt(0)
